# permlane32_swap replaces the cross-half LDS hop in residual epilogue row sums
# baseline (speedup 1.0000x reference)
; __device__ __forceinline__ unsigned cvt_pk_bf16(float lo, float hi) { unsigned r; asm volatile("v_cvt_pk_bf16_f32 %0, %1, %2" : "=v"(r) : "v"(lo), "v"(hi)); return r; }
;     __device__ __forceinline__ void operator()(const f32x4 (&acc)[2][2][4][2], const Unit& u, int wr, int wc, int fr, int fq, LAS unsigned char* lds, int tid, int ui, const Unit& nxt, bool has_next) const {
;     ...
;             for (int m = 0; m < 4; ++m) {
;                 const int row = row0 + ai * 128 + m * 16; const size_t off = (size_t)row * D + col0;
;                 typedef float f32x2 __attribute__((ext_vector_type(2)));
;                 f32x2 sq2 = (f32x2){0.f, 0.f};
; #pragma unroll
;                 for (int bj = 0; bj < 2; ++bj) {
;                     f32x2 v[4];
;                     const u32x4 w0 = xr[m][bj];
; #pragma unroll
;                     for (int i = 0; i < 4; ++i) v[i] = (f32x2){__uint_as_float(w0[i] << 16), __uint_as_float(w0[i] & 0xffff0000u)};
;                     const f32x2 al2 = (f32x2){alpha, alpha};
;                     unsigned wv[4];
; #pragma unroll
;                     for (int i = 0; i < 4; ++i) {
;                         const f32x4 av = acc[ai][bj][m][i >> 1], bb = bv[bj][i >> 1];
;                         const f32x2 a2 = (i & 1) ? (f32x2){av.z, av.w} : (f32x2){av.x, av.y}, b2 = (i & 1) ? (f32x2){bb.z, bb.w} : (f32x2){bb.x, bb.y};
;                         v[i] = __builtin_elementwise_fma(a2, al2, v[i]) + b2;
;                         sq2 = __builtin_elementwise_fma(v[i], v[i], sq2);
;                         wv[i] = cvt_pk_bf16(v[i].x, v[i].y);
;                     }
;                     u32x4 w; w.x = wv[0]; w.y = wv[1]; w.z = wv[2]; w.w = wv[3];
;                     *(u32x4*)(xb + off + bj * 128) = w;
;                 }
;                 float sq = sq2.x + sq2.y;
;                 sq += __shfl_xor(sq, 16); sq += __shfl_xor(sq, 32);
;                 if (fq == 0) ssp[(size_t)row * 16 + u.pn * 4 + wc] = sq;
.Lmy_epibar_resid:
	v_lshlrev_b32_e32 v216, 16, v172
	v_and_b32_e32 v217, 0xffff0000, v172
	v_lshlrev_b32_e32 v172, 16, v173
	v_and_b32_e32 v173, 0xffff0000, v173
	v_lshlrev_b32_e32 v242, 16, v170
	v_and_b32_e32 v243, 0xffff0000, v170
	v_lshlrev_b32_e32 v170, 16, v171
	v_and_b32_e32 v171, 0xffff0000, v171
	v_pk_fma_f32 v[140:141], v[140:141], s[26:27], v[216:217]
	v_lshlrev_b32_e32 v238, 16, v174
	v_and_b32_e32 v239, 0xffff0000, v174
	v_pk_fma_f32 v[142:143], v[142:143], s[26:27], v[172:173]
	v_pk_fma_f32 v[130:131], v[130:131], s[26:27], v[170:171]
	v_pk_add_f32 v[140:141], v[76:77], v[140:141]
	v_lshlrev_b32_e32 v174, 16, v175
	v_and_b32_e32 v175, 0xffff0000, v175
	v_pk_fma_f32 v[136:137], v[136:137], s[26:27], v[238:239]
	v_pk_add_f32 v[142:143], v[78:79], v[142:143]
	v_pk_add_f32 v[170:171], v[66:67], v[130:131]
	v_pk_fma_f32 v[130:131], v[140:141], v[140:141], 0 op_sel_hi:[1,1,0]
	v_lshlrev_b32_e32 v240, 16, v168
	v_and_b32_e32 v241, 0xffff0000, v168
	v_pk_fma_f32 v[138:139], v[138:139], s[26:27], v[174:175]
	v_pk_add_f32 v[136:137], v[68:69], v[136:137]
	v_pk_fma_f32 v[130:131], v[142:143], v[142:143], v[130:131]
	v_lshlrev_b32_e32 v168, 16, v169
	v_and_b32_e32 v169, 0xffff0000, v169
	v_pk_fma_f32 v[132:133], v[132:133], s[26:27], v[240:241]
	v_pk_add_f32 v[138:139], v[70:71], v[138:139]
	v_pk_fma_f32 v[130:131], v[136:137], v[136:137], v[130:131]
	v_pk_fma_f32 v[134:135], v[134:135], s[26:27], v[168:169]
	v_pk_add_f32 v[132:133], v[72:73], v[132:133]
	v_pk_fma_f32 v[130:131], v[138:139], v[138:139], v[130:131]
	v_pk_fma_f32 v[128:129], v[128:129], s[26:27], v[242:243]
	v_pk_add_f32 v[134:135], v[74:75], v[134:135]
	v_pk_fma_f32 v[130:131], v[132:133], v[132:133], v[130:131]
	v_pk_add_f32 v[168:169], v[64:65], v[128:129]
	v_pk_fma_f32 v[130:131], v[134:135], v[134:135], v[130:131]
	v_cvt_pk_bf16_f32 v128, v140, v141
	v_cndmask_b32_e32 v221, v224, v231, vcc
	v_pk_fma_f32 v[130:131], v[168:169], v[168:169], v[130:131]
	v_cvt_pk_bf16_f32 v129, v142, v143
	s_nop 0
	v_pk_fma_f32 v[130:131], v[170:171], v[170:171], v[130:131]
	s_nop 0
	v_add_f32_e32 v140, v130, v131
	ds_bpermute_b32 v141, v237, v140
	v_cvt_pk_bf16_f32 v130, v136, v137
	v_cvt_pk_bf16_f32 v131, v138, v139
	global_store_dwordx4 v[214:215], v[128:131], off
	v_cvt_pk_bf16_f32 v132, v132, v133
	v_cvt_pk_bf16_f32 v133, v134, v135
	v_cvt_pk_bf16_f32 v134, v168, v169
	v_cvt_pk_bf16_f32 v135, v170, v171
	global_store_dwordx4 v[214:215], v[132:135], off offset:256
	s_waitcnt lgkmcnt(0)
	v_add_f32_e32 v129, v140, v141
	v_lshlrev_b32_e32 v128, 2, v221
	v_mov_b32_e32 v130, v129
	s_nop 1
	v_permlane32_swap_b32_e32 v129, v130
	s_and_saveexec_b64 s[4:5], s[38:39]
	s_cbranch_execz .LBB0_206
	v_lshlrev_b64 v[132:133], 6, v[200:201]
	v_lshl_add_u64 v[132:133], s[48:49], 0, v[132:133]
	v_lshl_add_u64 v[132:133], s[42:43], 2, v[132:133]
	s_lshl_b32 s2, s62, 2
	v_lshl_add_u64 v[132:133], v[132:133], 0, s[2:3]
	s_waitcnt lgkmcnt(0)
	v_add_f32_e32 v129, v129, v130
	global_store_dword v[132:133], v129, off
.LBB0_206:
	s_or_b64 exec, exec, s[4:5]
	s_waitcnt lgkmcnt(0)
	v_lshlrev_b32_e32 v130, 16, v164
	v_and_b32_e32 v131, 0xffff0000, v164
	v_lshlrev_b32_e32 v132, 16, v165
	v_and_b32_e32 v133, 0xffff0000, v165
	v_pk_fma_f32 v[124:125], v[124:125], s[26:27], v[130:131]
	v_lshlrev_b32_e32 v134, 16, v166
	v_and_b32_e32 v135, 0xffff0000, v166
	v_pk_add_f32 v[124:125], v[76:77], v[124:125]
	v_pk_fma_f32 v[126:127], v[126:127], s[26:27], v[132:133]
	v_pk_fma_f32 v[130:131], v[124:125], v[124:125], 0 op_sel_hi:[1,1,0]
	v_pk_add_f32 v[126:127], v[78:79], v[126:127]
	v_pk_fma_f32 v[120:121], v[120:121], s[26:27], v[134:135]
	v_lshlrev_b32_e32 v136, 16, v167
	v_and_b32_e32 v137, 0xffff0000, v167
	v_pk_fma_f32 v[130:131], v[126:127], v[126:127], v[130:131]
	v_pk_add_f32 v[120:121], v[68:69], v[120:121]
	v_cvt_pk_bf16_f32 v124, v124, v125
	v_cvt_pk_bf16_f32 v125, v126, v127
	v_lshlrev_b32_e32 v132, 16, v162
	v_pk_fma_f32 v[130:131], v[120:121], v[120:121], v[130:131]
	v_cvt_pk_bf16_f32 v126, v120, v121
	v_pk_fma_f32 v[120:121], v[122:123], s[26:27], v[136:137]
	v_and_b32_e32 v133, 0xffff0000, v162
	v_pk_add_f32 v[120:121], v[70:71], v[120:121]
	v_lshlrev_b32_e32 v134, 16, v163
	v_pk_fma_f32 v[122:123], v[120:121], v[120:121], v[130:131]
	v_cvt_pk_bf16_f32 v127, v120, v121
	v_lshlrev_b32_e32 v120, 16, v160
	v_and_b32_e32 v121, 0xffff0000, v160
	v_lshlrev_b32_e32 v130, 16, v161
	v_and_b32_e32 v131, 0xffff0000, v161
	v_pk_fma_f32 v[116:117], v[116:117], s[26:27], v[120:121]
	v_pk_fma_f32 v[118:119], v[118:119], s[26:27], v[130:131]
	v_pk_add_f32 v[116:117], v[72:73], v[116:117]
	v_and_b32_e32 v135, 0xffff0000, v163
	v_pk_fma_f32 v[120:121], v[116:117], v[116:117], v[122:123]
	v_pk_add_f32 v[118:119], v[74:75], v[118:119]
	v_pk_fma_f32 v[112:113], v[112:113], s[26:27], v[132:133]
	v_pk_fma_f32 v[120:121], v[118:119], v[118:119], v[120:121]
	v_pk_add_f32 v[122:123], v[64:65], v[112:113]
	v_pk_fma_f32 v[114:115], v[114:115], s[26:27], v[134:135]
	v_pk_fma_f32 v[112:113], v[122:123], v[122:123], v[120:121]
	v_pk_add_f32 v[120:121], v[66:67], v[114:115]
	s_nop 0
	v_pk_fma_f32 v[112:113], v[120:121], v[120:121], v[112:113]
	s_nop 0
	v_add_f32_e32 v115, v112, v113
	ds_bpermute_b32 v129, v237, v115
	v_lshl_add_u64 v[112:113], s[82:83], 0, v[212:213]
	v_lshl_add_u64 v[130:131], v[196:197], 1, v[112:113]
	global_store_dwordx4 v[130:131], v[124:127], off
	v_cvt_pk_bf16_f32 v114, v116, v117
	s_waitcnt lgkmcnt(0)
	v_add_f32_e32 v112, v115, v129
	v_mov_b32_e32 v113, v112
	s_nop 1
	v_permlane32_swap_b32_e32 v112, v113
	v_cvt_pk_bf16_f32 v115, v118, v119
	v_cvt_pk_bf16_f32 v116, v122, v123
	v_cvt_pk_bf16_f32 v117, v120, v121
	global_store_dwordx4 v[130:131], v[114:117], off offset:256
	s_and_saveexec_b64 s[4:5], s[38:39]
	s_cbranch_execz .LBB0_208
	v_lshlrev_b64 v[114:115], 6, v[210:211]
	v_lshl_add_u64 v[114:115], s[48:49], 0, v[114:115]
	v_lshl_add_u64 v[114:115], s[42:43], 2, v[114:115]
	s_lshl_b32 s2, s62, 2
	v_lshl_add_u64 v[114:115], v[114:115], 0, s[2:3]
	s_waitcnt lgkmcnt(0)
	v_add_f32_e32 v112, v112, v113
	global_store_dword v[114:115], v112, off
; __device__ __forceinline__ unsigned cvt_pk_bf16(float lo, float hi) { unsigned r; asm volatile("v_cvt_pk_bf16_f32 %0, %1, %2" : "=v"(r) : "v"(lo), "v"(hi)); return r; }
;     __device__ __forceinline__ void operator()(const f32x4 (&acc)[2][2][4][2], const Unit& u, int wr, int wc, int fr, int fq, LAS unsigned char* lds, int tid, int ui, const Unit& nxt, bool has_next) const {
;     ...
;             for (int m = 0; m < 4; ++m) {
;                 const int row = row0 + ai * 128 + m * 16; const size_t off = (size_t)row * D + col0;
;                 typedef float f32x2 __attribute__((ext_vector_type(2)));
;                 f32x2 sq2 = (f32x2){0.f, 0.f};
; #pragma unroll
;                 for (int bj = 0; bj < 2; ++bj) {
;                     f32x2 v[4];
;                     const u32x4 w0 = xr[m][bj];
; #pragma unroll
;                     for (int i = 0; i < 4; ++i) v[i] = (f32x2){__uint_as_float(w0[i] << 16), __uint_as_float(w0[i] & 0xffff0000u)};
;                     const f32x2 al2 = (f32x2){alpha, alpha};
;                     unsigned wv[4];
; #pragma unroll
;                     for (int i = 0; i < 4; ++i) {
;                         const f32x4 av = acc[ai][bj][m][i >> 1], bb = bv[bj][i >> 1];
;                         const f32x2 a2 = (i & 1) ? (f32x2){av.z, av.w} : (f32x2){av.x, av.y}, b2 = (i & 1) ? (f32x2){bb.z, bb.w} : (f32x2){bb.x, bb.y};
;                         v[i] = __builtin_elementwise_fma(a2, al2, v[i]) + b2;
;                         sq2 = __builtin_elementwise_fma(v[i], v[i], sq2);
;                         wv[i] = cvt_pk_bf16(v[i].x, v[i].y);
;                     }
;                     u32x4 w; w.x = wv[0]; w.y = wv[1]; w.z = wv[2]; w.w = wv[3];
;                     *(u32x4*)(xb + off + bj * 128) = w;
;                 }
;                 float sq = sq2.x + sq2.y;
;                 sq += __shfl_xor(sq, 16); sq += __shfl_xor(sq, 32);
;                 if (fq == 0) ssp[(size_t)row * 16 + u.pn * 4 + wc] = sq;
.LBB0_208:
	s_or_b64 exec, exec, s[4:5]
	v_lshlrev_b32_e32 v112, 16, v156
	s_waitcnt lgkmcnt(0)
	v_and_b32_e32 v113, 0xffff0000, v156
	v_lshlrev_b32_e32 v114, 16, v157
	v_and_b32_e32 v115, 0xffff0000, v157
	v_pk_fma_f32 v[108:109], v[108:109], s[26:27], v[112:113]
	v_lshlrev_b32_e32 v116, 16, v158
	v_and_b32_e32 v117, 0xffff0000, v158
	v_pk_add_f32 v[108:109], v[76:77], v[108:109]
	v_pk_fma_f32 v[110:111], v[110:111], s[26:27], v[114:115]
	v_pk_fma_f32 v[112:113], v[108:109], v[108:109], 0 op_sel_hi:[1,1,0]
	v_pk_add_f32 v[110:111], v[78:79], v[110:111]
	v_pk_fma_f32 v[104:105], v[104:105], s[26:27], v[116:117]
	v_lshlrev_b32_e32 v118, 16, v159
	v_and_b32_e32 v119, 0xffff0000, v159
	v_pk_fma_f32 v[112:113], v[110:111], v[110:111], v[112:113]
	v_pk_add_f32 v[104:105], v[68:69], v[104:105]
	v_cvt_pk_bf16_f32 v108, v108, v109
	v_cvt_pk_bf16_f32 v109, v110, v111
	v_lshlrev_b32_e32 v114, 16, v154
	v_pk_fma_f32 v[112:113], v[104:105], v[104:105], v[112:113]
	v_cvt_pk_bf16_f32 v110, v104, v105
	v_pk_fma_f32 v[104:105], v[106:107], s[26:27], v[118:119]
	v_and_b32_e32 v115, 0xffff0000, v154
	v_pk_add_f32 v[104:105], v[70:71], v[104:105]
	v_lshlrev_b32_e32 v116, 16, v155
	v_pk_fma_f32 v[106:107], v[104:105], v[104:105], v[112:113]
	v_cvt_pk_bf16_f32 v111, v104, v105
	v_lshlrev_b32_e32 v104, 16, v152
	v_and_b32_e32 v105, 0xffff0000, v152
	v_lshlrev_b32_e32 v112, 16, v153
	v_and_b32_e32 v113, 0xffff0000, v153
	v_pk_fma_f32 v[100:101], v[100:101], s[26:27], v[104:105]
	v_pk_fma_f32 v[102:103], v[102:103], s[26:27], v[112:113]
	v_pk_add_f32 v[100:101], v[72:73], v[100:101]
	v_and_b32_e32 v117, 0xffff0000, v155
	v_pk_fma_f32 v[104:105], v[100:101], v[100:101], v[106:107]
	v_pk_add_f32 v[102:103], v[74:75], v[102:103]
	v_pk_fma_f32 v[96:97], v[96:97], s[26:27], v[114:115]
	v_pk_fma_f32 v[104:105], v[102:103], v[102:103], v[104:105]
	v_pk_add_f32 v[106:107], v[64:65], v[96:97]
	v_pk_fma_f32 v[98:99], v[98:99], s[26:27], v[116:117]
	v_pk_fma_f32 v[96:97], v[106:107], v[106:107], v[104:105]
	v_pk_add_f32 v[104:105], v[66:67], v[98:99]
	s_nop 0
	v_pk_fma_f32 v[96:97], v[104:105], v[104:105], v[96:97]
	s_nop 0
	v_add_f32_e32 v99, v96, v97
	ds_bpermute_b32 v114, v237, v99
	v_lshl_add_u64 v[96:97], s[82:83], 0, v[208:209]
	v_lshl_add_u64 v[112:113], v[196:197], 1, v[96:97]
	global_store_dwordx4 v[112:113], v[108:111], off
	v_cvt_pk_bf16_f32 v98, v100, v101
	s_waitcnt lgkmcnt(0)
	v_add_f32_e32 v96, v99, v114
	v_mov_b32_e32 v97, v96
	s_nop 1
	v_permlane32_swap_b32_e32 v96, v97
	v_cvt_pk_bf16_f32 v99, v102, v103
	v_cvt_pk_bf16_f32 v100, v106, v107
	v_cvt_pk_bf16_f32 v101, v104, v105
	global_store_dwordx4 v[112:113], v[98:101], off offset:256
	s_and_saveexec_b64 s[4:5], s[38:39]
	s_cbranch_execz .LBB0_210
	v_lshlrev_b64 v[98:99], 6, v[206:207]
	v_lshl_add_u64 v[98:99], s[48:49], 0, v[98:99]
	v_lshl_add_u64 v[98:99], s[42:43], 2, v[98:99]
	s_lshl_b32 s2, s62, 2
	v_lshl_add_u64 v[98:99], v[98:99], 0, s[2:3]
	s_waitcnt lgkmcnt(0)
	v_add_f32_e32 v96, v96, v97
	global_store_dword v[98:99], v96, off
.LBB0_210:
	s_or_b64 exec, exec, s[4:5]
	v_lshlrev_b32_e32 v96, 16, v148
	s_waitcnt lgkmcnt(0)
	v_and_b32_e32 v97, 0xffff0000, v148
	v_lshlrev_b32_e32 v98, 16, v149
	v_and_b32_e32 v99, 0xffff0000, v149
	v_pk_fma_f32 v[92:93], v[92:93], s[26:27], v[96:97]
	v_lshlrev_b32_e32 v100, 16, v150
	v_and_b32_e32 v101, 0xffff0000, v150
	v_pk_add_f32 v[92:93], v[76:77], v[92:93]
	v_pk_fma_f32 v[94:95], v[94:95], s[26:27], v[98:99]
	v_pk_fma_f32 v[96:97], v[92:93], v[92:93], 0 op_sel_hi:[1,1,0]
	v_pk_add_f32 v[94:95], v[78:79], v[94:95]
	v_pk_fma_f32 v[88:89], v[88:89], s[26:27], v[100:101]
	v_lshlrev_b32_e32 v102, 16, v151
	v_and_b32_e32 v103, 0xffff0000, v151
	v_pk_fma_f32 v[96:97], v[94:95], v[94:95], v[96:97]
	v_pk_add_f32 v[88:89], v[68:69], v[88:89]
	v_cvt_pk_bf16_f32 v92, v92, v93
	v_cvt_pk_bf16_f32 v93, v94, v95
	v_lshlrev_b32_e32 v98, 16, v146
	v_pk_fma_f32 v[96:97], v[88:89], v[88:89], v[96:97]
	v_cvt_pk_bf16_f32 v94, v88, v89
	v_pk_fma_f32 v[88:89], v[90:91], s[26:27], v[102:103]
	v_and_b32_e32 v99, 0xffff0000, v146
	v_pk_add_f32 v[88:89], v[70:71], v[88:89]
	v_lshlrev_b32_e32 v100, 16, v147
	v_pk_fma_f32 v[90:91], v[88:89], v[88:89], v[96:97]
	v_cvt_pk_bf16_f32 v95, v88, v89
	v_lshlrev_b32_e32 v88, 16, v144
	v_and_b32_e32 v89, 0xffff0000, v144
	v_lshlrev_b32_e32 v96, 16, v145
	v_and_b32_e32 v97, 0xffff0000, v145
	v_pk_fma_f32 v[84:85], v[84:85], s[26:27], v[88:89]
	v_pk_fma_f32 v[86:87], v[86:87], s[26:27], v[96:97]
	v_pk_add_f32 v[84:85], v[72:73], v[84:85]
	v_and_b32_e32 v101, 0xffff0000, v147
	v_pk_fma_f32 v[88:89], v[84:85], v[84:85], v[90:91]
	v_pk_add_f32 v[86:87], v[74:75], v[86:87]
	v_pk_fma_f32 v[80:81], v[80:81], s[26:27], v[98:99]
	v_pk_fma_f32 v[88:89], v[86:87], v[86:87], v[88:89]
	v_pk_add_f32 v[90:91], v[64:65], v[80:81]
	v_pk_fma_f32 v[82:83], v[82:83], s[26:27], v[100:101]
	v_pk_fma_f32 v[80:81], v[90:91], v[90:91], v[88:89]
	v_pk_add_f32 v[88:89], v[66:67], v[82:83]
	s_nop 0
	v_pk_fma_f32 v[80:81], v[88:89], v[88:89], v[80:81]
	s_nop 0
	v_add_f32_e32 v83, v80, v81
	ds_bpermute_b32 v98, v237, v83
	v_lshl_add_u64 v[80:81], s[82:83], 0, v[204:205]
	v_lshl_add_u64 v[96:97], v[196:197], 1, v[80:81]
	global_store_dwordx4 v[96:97], v[92:95], off
	v_cvt_pk_bf16_f32 v82, v84, v85
	s_waitcnt lgkmcnt(0)
	v_add_f32_e32 v80, v83, v98
	v_mov_b32_e32 v81, v80
	s_nop 1
	v_permlane32_swap_b32_e32 v80, v81
	v_cvt_pk_bf16_f32 v83, v86, v87
	v_cvt_pk_bf16_f32 v84, v90, v91
	v_cvt_pk_bf16_f32 v85, v88, v89
	global_store_dwordx4 v[96:97], v[82:85], off offset:256
	s_and_saveexec_b64 s[4:5], s[38:39]
	s_cbranch_execz .LBB0_212
	v_lshlrev_b64 v[82:83], 6, v[202:203]
	v_lshl_add_u64 v[82:83], s[48:49], 0, v[82:83]
	v_lshl_add_u64 v[82:83], s[42:43], 2, v[82:83]
	s_lshl_b32 s2, s62, 2
	v_lshl_add_u64 v[82:83], v[82:83], 0, s[2:3]
	s_waitcnt lgkmcnt(0)
	v_add_f32_e32 v80, v80, v81
	global_store_dword v[82:83], v80, off
; __device__ __forceinline__ unsigned cvt_pk_bf16(float lo, float hi) { unsigned r; asm volatile("v_cvt_pk_bf16_f32 %0, %1, %2" : "=v"(r) : "v"(lo), "v"(hi)); return r; }
;     __device__ __forceinline__ void operator()(const f32x4 (&acc)[2][2][4][2], const Unit& u, int wr, int wc, int fr, int fq, LAS unsigned char* lds, int tid, int ui, const Unit& nxt, bool has_next) const {
;     ...
;         for (int ai = 0; ai < 2; ++ai) {
;             u32x4 xr[4][2];
; #pragma unroll
;             for (int m = 0; m < 4; ++m)
; #pragma unroll
;                 for (int bj = 0; bj < 2; ++bj) xr[m][bj] = *(const u32x4*)(xb + (size_t)(row0 + ai * 128 + m * 16) * D + col0 + bj * 128);
; #pragma unroll
;             for (int m = 0; m < 4; ++m) {
;                 const int row = row0 + ai * 128 + m * 16; const size_t off = (size_t)row * D + col0;
;                 typedef float f32x2 __attribute__((ext_vector_type(2)));
;                 f32x2 sq2 = (f32x2){0.f, 0.f};
; #pragma unroll
;                 for (int bj = 0; bj < 2; ++bj) {
;                     f32x2 v[4];
;                     const u32x4 w0 = xr[m][bj];
; #pragma unroll
;                     for (int i = 0; i < 4; ++i) v[i] = (f32x2){__uint_as_float(w0[i] << 16), __uint_as_float(w0[i] & 0xffff0000u)};
;                     const f32x2 al2 = (f32x2){alpha, alpha};
;                     unsigned wv[4];
; #pragma unroll
;                     for (int i = 0; i < 4; ++i) {
;                         const f32x4 av = acc[ai][bj][m][i >> 1], bb = bv[bj][i >> 1];
;                         const f32x2 a2 = (i & 1) ? (f32x2){av.z, av.w} : (f32x2){av.x, av.y}, b2 = (i & 1) ? (f32x2){bb.z, bb.w} : (f32x2){bb.x, bb.y};
;                         v[i] = __builtin_elementwise_fma(a2, al2, v[i]) + b2;
;                         sq2 = __builtin_elementwise_fma(v[i], v[i], sq2);
;                         wv[i] = cvt_pk_bf16(v[i].x, v[i].y);
;                     }
;                     u32x4 w; w.x = wv[0]; w.y = wv[1]; w.z = wv[2]; w.w = wv[3];
;                     *(u32x4*)(xb + off + bj * 128) = w;
;                 }
;                 float sq = sq2.x + sq2.y;
;                 sq += __shfl_xor(sq, 16); sq += __shfl_xor(sq, 32);
;                 if (fq == 0) ssp[(size_t)row * 16 + u.pn * 4 + wc] = sq;
.LBB0_212:
	s_or_b64 exec, exec, s[4:5]
	v_add_u32_e32 v116, 0x80, v200
	v_ashrrev_i32_e32 v117, 31, v116
	v_lshlrev_b64 v[126:127], 11, v[116:117]
	s_waitcnt lgkmcnt(0)
	v_lshl_add_u64 v[80:81], v[198:199], 0, v[126:127]
	global_load_dwordx4 v[118:121], v[80:81], off
	global_load_dwordx4 v[122:125], v[80:81], off offset:256
	v_add_u32_e32 v112, 0x90, v200
	v_ashrrev_i32_e32 v113, 31, v112
	v_add_u32_e32 v108, 0xa0, v200
	v_lshlrev_b64 v[114:115], 11, v[112:113]
	v_ashrrev_i32_e32 v109, 31, v108
	v_add_u32_e32 v104, 0xb0, v200
	v_lshl_add_u64 v[80:81], v[198:199], 0, v[114:115]
	v_lshlrev_b64 v[110:111], 11, v[108:109]
	v_ashrrev_i32_e32 v105, 31, v104
	global_load_dwordx4 v[100:103], v[80:81], off
	global_load_dwordx4 v[96:99], v[80:81], off offset:256
	v_lshl_add_u64 v[80:81], v[198:199], 0, v[110:111]
	v_lshlrev_b64 v[106:107], 11, v[104:105]
	global_load_dwordx4 v[92:95], v[80:81], off
	global_load_dwordx4 v[88:91], v[80:81], off offset:256
	v_lshl_add_u64 v[80:81], v[198:199], 0, v[106:107]
	global_load_dwordx4 v[84:87], v[80:81], off
	s_nop 0
	global_load_dwordx4 v[80:83], v[80:81], off offset:256
	s_waitcnt vmcnt(7)
	v_lshlrev_b32_e32 v130, 16, v118
	v_and_b32_e32 v131, 0xffff0000, v118
	v_lshlrev_b32_e32 v118, 16, v119
	v_and_b32_e32 v119, 0xffff0000, v119
	v_pk_fma_f32 v[60:61], v[60:61], s[26:27], v[130:131]
	v_lshlrev_b32_e32 v132, 16, v120
	v_and_b32_e32 v133, 0xffff0000, v120
	v_pk_add_f32 v[60:61], v[76:77], v[60:61]
	v_pk_fma_f32 v[62:63], v[62:63], s[26:27], v[118:119]
	v_pk_fma_f32 v[130:131], v[60:61], v[60:61], 0 op_sel_hi:[1,1,0]
	v_pk_add_f32 v[62:63], v[78:79], v[62:63]
	v_pk_fma_f32 v[56:57], v[56:57], s[26:27], v[132:133]
	v_lshlrev_b32_e32 v120, 16, v121
	v_and_b32_e32 v121, 0xffff0000, v121
	v_pk_fma_f32 v[118:119], v[62:63], v[62:63], v[130:131]
	v_pk_add_f32 v[56:57], v[68:69], v[56:57]
	v_cvt_pk_bf16_f32 v60, v60, v61
	v_cvt_pk_bf16_f32 v61, v62, v63
	s_nop 0
	v_pk_fma_f32 v[118:119], v[56:57], v[56:57], v[118:119]
	v_cvt_pk_bf16_f32 v62, v56, v57
	v_pk_fma_f32 v[56:57], v[58:59], s[26:27], v[120:121]
	s_waitcnt vmcnt(6)
	v_lshlrev_b32_e32 v120, 16, v125
	v_pk_add_f32 v[56:57], v[70:71], v[56:57]
	v_and_b32_e32 v121, 0xffff0000, v125
	v_pk_fma_f32 v[58:59], v[56:57], v[56:57], v[118:119]
	v_cvt_pk_bf16_f32 v63, v56, v57
	v_lshl_add_u64 v[56:57], s[82:83], 0, v[126:127]
	v_lshl_add_u64 v[56:57], v[196:197], 1, v[56:57]
	global_store_dwordx4 v[56:57], v[60:63], off
	v_lshlrev_b32_e32 v118, 16, v124
	v_and_b32_e32 v119, 0xffff0000, v124
	v_lshlrev_b32_e32 v60, 16, v122
	v_and_b32_e32 v61, 0xffff0000, v122
	v_lshlrev_b32_e32 v62, 16, v123
	v_and_b32_e32 v63, 0xffff0000, v123
	v_pk_fma_f32 v[52:53], v[52:53], s[26:27], v[60:61]
	v_pk_fma_f32 v[54:55], v[54:55], s[26:27], v[62:63]
	v_pk_add_f32 v[52:53], v[72:73], v[52:53]
	v_pk_add_f32 v[54:55], v[74:75], v[54:55]
	v_pk_fma_f32 v[58:59], v[52:53], v[52:53], v[58:59]
	v_pk_fma_f32 v[48:49], v[48:49], s[26:27], v[118:119]
	v_pk_fma_f32 v[58:59], v[54:55], v[54:55], v[58:59]
	v_pk_add_f32 v[48:49], v[64:65], v[48:49]
	v_cvt_pk_bf16_f32 v52, v52, v53
	v_cvt_pk_bf16_f32 v53, v54, v55
	s_nop 0
	v_pk_fma_f32 v[58:59], v[48:49], v[48:49], v[58:59]
	v_cvt_pk_bf16_f32 v54, v48, v49
	v_pk_fma_f32 v[48:49], v[50:51], s[26:27], v[120:121]
	s_nop 0
	v_pk_add_f32 v[48:49], v[66:67], v[48:49]
	s_nop 0
	v_pk_fma_f32 v[50:51], v[48:49], v[48:49], v[58:59]
	v_cvt_pk_bf16_f32 v55, v48, v49
	global_store_dwordx4 v[56:57], v[52:55], off offset:256
	v_add_f32_e32 v48, v50, v51
	ds_bpermute_b32 v49, v237, v48
	s_waitcnt lgkmcnt(0)
	v_add_f32_e32 v48, v48, v49
	v_mov_b32_e32 v49, v48
	s_nop 1
	v_permlane32_swap_b32_e32 v48, v49
	s_and_saveexec_b64 s[4:5], s[38:39]
	s_cbranch_execz .LBB0_214
	v_lshlrev_b64 v[50:51], 6, v[116:117]
	v_lshl_add_u64 v[50:51], s[48:49], 0, v[50:51]
	v_lshl_add_u64 v[50:51], s[42:43], 2, v[50:51]
	s_lshl_b32 s2, s62, 2
	v_lshl_add_u64 v[50:51], v[50:51], 0, s[2:3]
	s_waitcnt lgkmcnt(0)
	v_add_f32_e32 v48, v48, v49
	global_store_dword v[50:51], v48, off
.LBB0_214:
	s_or_b64 exec, exec, s[4:5]
	s_waitcnt vmcnt(7)
	v_lshlrev_b32_e32 v48, 16, v100
	s_waitcnt lgkmcnt(0)
	v_and_b32_e32 v49, 0xffff0000, v100
	v_lshlrev_b32_e32 v50, 16, v101
	v_and_b32_e32 v51, 0xffff0000, v101
	v_pk_fma_f32 v[44:45], v[44:45], s[26:27], v[48:49]
	v_lshlrev_b32_e32 v52, 16, v102
	v_and_b32_e32 v53, 0xffff0000, v102
	v_pk_add_f32 v[44:45], v[76:77], v[44:45]
	v_pk_fma_f32 v[46:47], v[46:47], s[26:27], v[50:51]
	v_pk_fma_f32 v[48:49], v[44:45], v[44:45], 0 op_sel_hi:[1,1,0]
	v_pk_add_f32 v[46:47], v[78:79], v[46:47]
	v_pk_fma_f32 v[40:41], v[40:41], s[26:27], v[52:53]
	v_lshlrev_b32_e32 v54, 16, v103
	v_and_b32_e32 v55, 0xffff0000, v103
	v_pk_fma_f32 v[48:49], v[46:47], v[46:47], v[48:49]
	v_pk_add_f32 v[40:41], v[68:69], v[40:41]
	v_cvt_pk_bf16_f32 v44, v44, v45
	v_cvt_pk_bf16_f32 v45, v46, v47
	s_waitcnt vmcnt(6)
	v_lshlrev_b32_e32 v50, 16, v98
	v_pk_fma_f32 v[48:49], v[40:41], v[40:41], v[48:49]
	v_cvt_pk_bf16_f32 v46, v40, v41
	v_pk_fma_f32 v[40:41], v[42:43], s[26:27], v[54:55]
	v_and_b32_e32 v51, 0xffff0000, v98
	v_pk_add_f32 v[40:41], v[70:71], v[40:41]
	v_lshlrev_b32_e32 v52, 16, v99
	v_pk_fma_f32 v[42:43], v[40:41], v[40:41], v[48:49]
	v_cvt_pk_bf16_f32 v47, v40, v41
	v_lshlrev_b32_e32 v40, 16, v96
	v_and_b32_e32 v41, 0xffff0000, v96
	v_lshlrev_b32_e32 v48, 16, v97
	v_and_b32_e32 v49, 0xffff0000, v97
	v_pk_fma_f32 v[36:37], v[36:37], s[26:27], v[40:41]
	v_pk_fma_f32 v[38:39], v[38:39], s[26:27], v[48:49]
	v_pk_add_f32 v[36:37], v[72:73], v[36:37]
	v_and_b32_e32 v53, 0xffff0000, v99
	v_pk_fma_f32 v[40:41], v[36:37], v[36:37], v[42:43]
	v_pk_add_f32 v[38:39], v[74:75], v[38:39]
	v_pk_fma_f32 v[32:33], v[32:33], s[26:27], v[50:51]
	v_pk_fma_f32 v[40:41], v[38:39], v[38:39], v[40:41]
	v_pk_add_f32 v[42:43], v[64:65], v[32:33]
	v_pk_fma_f32 v[34:35], v[34:35], s[26:27], v[52:53]
	v_pk_fma_f32 v[32:33], v[42:43], v[42:43], v[40:41]
	v_pk_add_f32 v[40:41], v[66:67], v[34:35]
	s_nop 0
	v_pk_fma_f32 v[32:33], v[40:41], v[40:41], v[32:33]
	s_nop 0
	v_add_f32_e32 v35, v32, v33
	ds_bpermute_b32 v50, v237, v35
	v_lshl_add_u64 v[32:33], s[82:83], 0, v[114:115]
	v_lshl_add_u64 v[48:49], v[196:197], 1, v[32:33]
	global_store_dwordx4 v[48:49], v[44:47], off
	v_cvt_pk_bf16_f32 v34, v36, v37
	s_waitcnt lgkmcnt(0)
	v_add_f32_e32 v32, v35, v50
	v_mov_b32_e32 v33, v32
	s_nop 1
	v_permlane32_swap_b32_e32 v32, v33
	v_cvt_pk_bf16_f32 v35, v38, v39
	v_cvt_pk_bf16_f32 v36, v42, v43
	v_cvt_pk_bf16_f32 v37, v40, v41
	global_store_dwordx4 v[48:49], v[34:37], off offset:256
	s_and_saveexec_b64 s[4:5], s[38:39]
	s_cbranch_execz .LBB0_216
	v_lshlrev_b64 v[34:35], 6, v[112:113]
	v_lshl_add_u64 v[34:35], s[48:49], 0, v[34:35]
	v_lshl_add_u64 v[34:35], s[42:43], 2, v[34:35]
	s_lshl_b32 s2, s62, 2
	v_lshl_add_u64 v[34:35], v[34:35], 0, s[2:3]
	s_waitcnt lgkmcnt(0)
	v_add_f32_e32 v32, v32, v33
	global_store_dword v[34:35], v32, off
; __device__ __forceinline__ unsigned cvt_pk_bf16(float lo, float hi) { unsigned r; asm volatile("v_cvt_pk_bf16_f32 %0, %1, %2" : "=v"(r) : "v"(lo), "v"(hi)); return r; }
;     __device__ __forceinline__ void operator()(const f32x4 (&acc)[2][2][4][2], const Unit& u, int wr, int wc, int fr, int fq, LAS unsigned char* lds, int tid, int ui, const Unit& nxt, bool has_next) const {
;     ...
;             for (int m = 0; m < 4; ++m) {
;                 const int row = row0 + ai * 128 + m * 16; const size_t off = (size_t)row * D + col0;
;                 typedef float f32x2 __attribute__((ext_vector_type(2)));
;                 f32x2 sq2 = (f32x2){0.f, 0.f};
; #pragma unroll
;                 for (int bj = 0; bj < 2; ++bj) {
;                     f32x2 v[4];
;                     const u32x4 w0 = xr[m][bj];
; #pragma unroll
;                     for (int i = 0; i < 4; ++i) v[i] = (f32x2){__uint_as_float(w0[i] << 16), __uint_as_float(w0[i] & 0xffff0000u)};
;                     const f32x2 al2 = (f32x2){alpha, alpha};
;                     unsigned wv[4];
; #pragma unroll
;                     for (int i = 0; i < 4; ++i) {
;                         const f32x4 av = acc[ai][bj][m][i >> 1], bb = bv[bj][i >> 1];
;                         const f32x2 a2 = (i & 1) ? (f32x2){av.z, av.w} : (f32x2){av.x, av.y}, b2 = (i & 1) ? (f32x2){bb.z, bb.w} : (f32x2){bb.x, bb.y};
;                         v[i] = __builtin_elementwise_fma(a2, al2, v[i]) + b2;
;                         sq2 = __builtin_elementwise_fma(v[i], v[i], sq2);
;                         wv[i] = cvt_pk_bf16(v[i].x, v[i].y);
;                     }
;                     u32x4 w; w.x = wv[0]; w.y = wv[1]; w.z = wv[2]; w.w = wv[3];
;                     *(u32x4*)(xb + off + bj * 128) = w;
;                 }
;                 float sq = sq2.x + sq2.y;
;                 sq += __shfl_xor(sq, 16); sq += __shfl_xor(sq, 32);
;                 if (fq == 0) ssp[(size_t)row * 16 + u.pn * 4 + wc] = sq;
.LBB0_216:
	s_or_b64 exec, exec, s[4:5]
	s_waitcnt vmcnt(7)
	v_lshlrev_b32_e32 v32, 16, v92
	s_waitcnt lgkmcnt(0)
	v_and_b32_e32 v33, 0xffff0000, v92
	v_lshlrev_b32_e32 v34, 16, v93
	v_and_b32_e32 v35, 0xffff0000, v93
	v_pk_fma_f32 v[28:29], v[28:29], s[26:27], v[32:33]
	v_lshlrev_b32_e32 v36, 16, v94
	v_and_b32_e32 v37, 0xffff0000, v94
	v_pk_add_f32 v[28:29], v[76:77], v[28:29]
	v_pk_fma_f32 v[30:31], v[30:31], s[26:27], v[34:35]
	v_pk_fma_f32 v[32:33], v[28:29], v[28:29], 0 op_sel_hi:[1,1,0]
	v_pk_add_f32 v[30:31], v[78:79], v[30:31]
	v_pk_fma_f32 v[24:25], v[24:25], s[26:27], v[36:37]
	v_lshlrev_b32_e32 v38, 16, v95
	v_and_b32_e32 v39, 0xffff0000, v95
	v_pk_fma_f32 v[32:33], v[30:31], v[30:31], v[32:33]
	v_pk_add_f32 v[24:25], v[68:69], v[24:25]
	v_cvt_pk_bf16_f32 v28, v28, v29
	v_cvt_pk_bf16_f32 v29, v30, v31
	s_waitcnt vmcnt(6)
	v_lshlrev_b32_e32 v34, 16, v90
	v_pk_fma_f32 v[32:33], v[24:25], v[24:25], v[32:33]
	v_cvt_pk_bf16_f32 v30, v24, v25
	v_pk_fma_f32 v[24:25], v[26:27], s[26:27], v[38:39]
	v_and_b32_e32 v35, 0xffff0000, v90
	v_pk_add_f32 v[24:25], v[70:71], v[24:25]
	v_lshlrev_b32_e32 v36, 16, v91
	v_pk_fma_f32 v[26:27], v[24:25], v[24:25], v[32:33]
	v_cvt_pk_bf16_f32 v31, v24, v25
	v_lshlrev_b32_e32 v24, 16, v88
	v_and_b32_e32 v25, 0xffff0000, v88
	v_lshlrev_b32_e32 v32, 16, v89
	v_and_b32_e32 v33, 0xffff0000, v89
	v_pk_fma_f32 v[20:21], v[20:21], s[26:27], v[24:25]
	v_pk_fma_f32 v[22:23], v[22:23], s[26:27], v[32:33]
	v_pk_add_f32 v[20:21], v[72:73], v[20:21]
	v_and_b32_e32 v37, 0xffff0000, v91
	v_pk_fma_f32 v[24:25], v[20:21], v[20:21], v[26:27]
	v_pk_add_f32 v[22:23], v[74:75], v[22:23]
	v_pk_fma_f32 v[16:17], v[16:17], s[26:27], v[34:35]
	v_pk_fma_f32 v[24:25], v[22:23], v[22:23], v[24:25]
	v_pk_add_f32 v[26:27], v[64:65], v[16:17]
	v_pk_fma_f32 v[18:19], v[18:19], s[26:27], v[36:37]
	v_pk_fma_f32 v[16:17], v[26:27], v[26:27], v[24:25]
	v_pk_add_f32 v[24:25], v[66:67], v[18:19]
	s_nop 0
	v_pk_fma_f32 v[16:17], v[24:25], v[24:25], v[16:17]
	s_nop 0
	v_add_f32_e32 v19, v16, v17
	ds_bpermute_b32 v34, v237, v19
	v_lshl_add_u64 v[16:17], s[82:83], 0, v[110:111]
	v_lshl_add_u64 v[32:33], v[196:197], 1, v[16:17]
	global_store_dwordx4 v[32:33], v[28:31], off
	v_cvt_pk_bf16_f32 v18, v20, v21
	s_waitcnt lgkmcnt(0)
	v_add_f32_e32 v16, v19, v34
	v_mov_b32_e32 v17, v16
	s_nop 1
	v_permlane32_swap_b32_e32 v16, v17
	v_cvt_pk_bf16_f32 v19, v22, v23
	v_cvt_pk_bf16_f32 v20, v26, v27
	v_cvt_pk_bf16_f32 v21, v24, v25
	global_store_dwordx4 v[32:33], v[18:21], off offset:256
	s_and_saveexec_b64 s[4:5], s[38:39]
	s_cbranch_execz .LBB0_218
	v_lshlrev_b64 v[18:19], 6, v[108:109]
	v_lshl_add_u64 v[18:19], s[48:49], 0, v[18:19]
	v_lshl_add_u64 v[18:19], s[42:43], 2, v[18:19]
	s_lshl_b32 s2, s62, 2
	v_lshl_add_u64 v[18:19], v[18:19], 0, s[2:3]
	s_waitcnt lgkmcnt(0)
	v_add_f32_e32 v16, v16, v17
	global_store_dword v[18:19], v16, off
.LBB0_218:
	s_or_b64 exec, exec, s[4:5]
	s_waitcnt vmcnt(7)
	v_lshlrev_b32_e32 v16, 16, v84
	s_waitcnt lgkmcnt(0)
	v_and_b32_e32 v17, 0xffff0000, v84
	v_lshlrev_b32_e32 v18, 16, v85
	v_and_b32_e32 v19, 0xffff0000, v85
	v_pk_fma_f32 v[12:13], v[12:13], s[26:27], v[16:17]
	v_lshlrev_b32_e32 v20, 16, v86
	v_and_b32_e32 v21, 0xffff0000, v86
	v_pk_add_f32 v[12:13], v[76:77], v[12:13]
	v_pk_fma_f32 v[14:15], v[14:15], s[26:27], v[18:19]
	v_pk_fma_f32 v[16:17], v[12:13], v[12:13], 0 op_sel_hi:[1,1,0]
	v_pk_add_f32 v[14:15], v[78:79], v[14:15]
	v_pk_fma_f32 v[8:9], v[8:9], s[26:27], v[20:21]
	v_lshlrev_b32_e32 v22, 16, v87
	v_and_b32_e32 v23, 0xffff0000, v87
	v_pk_fma_f32 v[16:17], v[14:15], v[14:15], v[16:17]
	v_pk_add_f32 v[8:9], v[68:69], v[8:9]
	v_cvt_pk_bf16_f32 v12, v12, v13
	v_cvt_pk_bf16_f32 v13, v14, v15
	s_waitcnt vmcnt(6)
	v_lshlrev_b32_e32 v18, 16, v82
	v_pk_fma_f32 v[16:17], v[8:9], v[8:9], v[16:17]
	v_cvt_pk_bf16_f32 v14, v8, v9
	v_pk_fma_f32 v[8:9], v[10:11], s[26:27], v[22:23]
	v_and_b32_e32 v19, 0xffff0000, v82
	v_pk_add_f32 v[8:9], v[70:71], v[8:9]
	v_lshlrev_b32_e32 v20, 16, v83
	v_pk_fma_f32 v[10:11], v[8:9], v[8:9], v[16:17]
	v_cvt_pk_bf16_f32 v15, v8, v9
	v_lshlrev_b32_e32 v8, 16, v80
	v_and_b32_e32 v9, 0xffff0000, v80
	v_lshlrev_b32_e32 v16, 16, v81
	v_and_b32_e32 v17, 0xffff0000, v81
	v_pk_fma_f32 v[4:5], v[4:5], s[26:27], v[8:9]
	v_pk_fma_f32 v[6:7], v[6:7], s[26:27], v[16:17]
	v_pk_add_f32 v[4:5], v[72:73], v[4:5]
	v_and_b32_e32 v21, 0xffff0000, v83
	v_pk_fma_f32 v[8:9], v[4:5], v[4:5], v[10:11]
	v_pk_add_f32 v[6:7], v[74:75], v[6:7]
	v_pk_fma_f32 v[0:1], v[0:1], s[26:27], v[18:19]
	v_pk_fma_f32 v[8:9], v[6:7], v[6:7], v[8:9]
	v_pk_add_f32 v[10:11], v[64:65], v[0:1]
	v_pk_fma_f32 v[2:3], v[2:3], s[26:27], v[20:21]
	v_pk_fma_f32 v[0:1], v[10:11], v[10:11], v[8:9]
	v_pk_add_f32 v[8:9], v[66:67], v[2:3]
	s_nop 0
	v_pk_fma_f32 v[0:1], v[8:9], v[8:9], v[0:1]
	s_nop 0
	v_add_f32_e32 v3, v0, v1
	ds_bpermute_b32 v18, v237, v3
	v_lshl_add_u64 v[0:1], s[82:83], 0, v[106:107]
	v_lshl_add_u64 v[16:17], v[196:197], 1, v[0:1]
	global_store_dwordx4 v[16:17], v[12:15], off
	v_cvt_pk_bf16_f32 v2, v4, v5
	s_waitcnt lgkmcnt(0)
	v_add_f32_e32 v0, v3, v18
	v_mov_b32_e32 v1, v0
	s_nop 1
	v_permlane32_swap_b32_e32 v0, v1
	v_cvt_pk_bf16_f32 v3, v6, v7
	v_cvt_pk_bf16_f32 v4, v10, v11
	v_cvt_pk_bf16_f32 v5, v8, v9
	global_store_dwordx4 v[16:17], v[2:5], off offset:256
	s_and_saveexec_b64 s[4:5], s[38:39]
	s_cbranch_execz .LBB0_220
	v_lshlrev_b64 v[2:3], 6, v[104:105]
	v_lshl_add_u64 v[2:3], s[48:49], 0, v[2:3]
	v_lshl_add_u64 v[2:3], s[42:43], 2, v[2:3]
	s_lshl_b32 s2, s62, 2
	v_lshl_add_u64 v[2:3], v[2:3], 0, s[2:3]
	s_waitcnt lgkmcnt(0)
	v_add_f32_e32 v0, v0, v1
	global_store_dword v[2:3], v0, off
